# MLA loop v2: persistent -m_ref accumulator-init block (no per-iteration 16 v_mov), one row-max per 64-key tile, exp in place: ~40 fewer VALU per wave-iteration; rest as v34
# speedup vs baseline: 1.0134x; 1.0123x over previous
.LBB0_376:
	s_max_i32 s20, s34, 1
	s_cmp_eq_u32 s20, 1
	s_waitcnt lgkmcnt(0)
	s_barrier
	s_cbranch_scc1 .LBB0_359
	v_lshlrev_b64 v[4:5], 7, v[86:87]
	v_and_b32_e32 v2, 7, v98
	v_lshl_add_u64 v[4:5], s[10:11], 0, v[4:5]
	v_lshlrev_b32_e32 v2, 4, v2
	v_lshl_add_u64 v[4:5], v[4:5], 0, v[2:3]
	v_lshlrev_b64 v[6:7], 11, v[84:85]
	v_and_b32_e32 v2, 15, v98
	v_lshl_add_u64 v[6:7], s[12:13], 0, v[6:7]
	v_lshlrev_b32_e32 v2, 4, v2
	s_or_b32 s36, s33, 2
	v_add_u32_e32 v19, v188, v99
	v_lshl_add_u64 v[6:7], v[6:7], 0, v[2:3]
	s_mov_b32 s37, -3
	v_xor_b32_e32 v210, 0x80000000, v192
	v_mov_b32_e32 v211, v210
	v_mov_b32_e32 v212, v210
	v_mov_b32_e32 v213, v210
	v_mov_b32_e32 v214, v210
	v_mov_b32_e32 v215, v210
	v_mov_b32_e32 v216, v210
	v_mov_b32_e32 v217, v210
	v_mov_b32_e32 v218, v210
	v_mov_b32_e32 v219, v210
	v_mov_b32_e32 v220, v210
	v_mov_b32_e32 v221, v210
	v_mov_b32_e32 v222, v210
	v_mov_b32_e32 v223, v210
	v_mov_b32_e32 v224, v210
	v_mov_b32_e32 v225, v210
	s_branch .LBB0_380

.Lm_noload:
	s_cmp_gt_i32 s20, s35
	s_cbranch_scc1 .LBB0_379
	s_bitcmp1_b32 s20, 0
	s_cselect_b32 s38, 0xb400, 0
	v_add_u32_e32 v8, s38, v191
	ds_read_b128 v[10:13], v8
	ds_read_b128 v[14:17], v8 offset:32
	ds_read_b128 v[202:205], v8 offset:64
	ds_read_b128 v[206:209], v8 offset:96
	v_add_u32_e32 v197, s38, v196
	s_setprio 3
	s_waitcnt lgkmcnt(3)
	v_mfma_f32_32x32x16_bf16 v[100:115], v[10:13], v[116:119], v[210:225]
	ds_read_b128 v[10:13], v8 offset:128
	s_waitcnt lgkmcnt(3)
	v_mfma_f32_32x32x16_bf16 v[100:115], v[14:17], v[120:123], v[100:115]
	ds_read_b128 v[14:17], v8 offset:160
	s_waitcnt lgkmcnt(3)
	v_mfma_f32_32x32x16_bf16 v[100:115], v[202:205], v[124:127], v[100:115]
	ds_read_b128 v[202:205], v8 offset:192
	s_waitcnt lgkmcnt(3)
	v_mfma_f32_32x32x16_bf16 v[100:115], v[206:209], v[132:135], v[100:115]
	ds_read_b128 v[206:209], v8 offset:224
	s_waitcnt lgkmcnt(3)
	v_mfma_f32_32x32x16_bf16 v[100:115], v[10:13], v[136:139], v[100:115]
	ds_read_b128 v[10:13], v8 offset:256
	s_waitcnt lgkmcnt(3)
	v_mfma_f32_32x32x16_bf16 v[100:115], v[14:17], v[140:143], v[100:115]
	ds_read_b128 v[14:17], v8 offset:288
	s_waitcnt lgkmcnt(3)
	v_mfma_f32_32x32x16_bf16 v[100:115], v[202:205], v[144:147], v[100:115]
	ds_read_b128 v[202:205], v8 offset:320
	s_waitcnt lgkmcnt(3)
	v_mfma_f32_32x32x16_bf16 v[100:115], v[206:209], v[148:151], v[100:115]
	ds_read_b128 v[206:209], v8 offset:352
	s_waitcnt lgkmcnt(3)
	v_mfma_f32_32x32x16_bf16 v[100:115], v[10:13], v[152:155], v[100:115]
	ds_read_b128 v[10:13], v8 offset:12800
	s_waitcnt lgkmcnt(3)
	v_mfma_f32_32x32x16_bf16 v[100:115], v[14:17], v[156:159], v[100:115]
	ds_read_b128 v[14:17], v8 offset:12832
	s_waitcnt lgkmcnt(3)
	v_mfma_f32_32x32x16_bf16 v[100:115], v[202:205], v[160:163], v[100:115]
	ds_read_b128 v[202:205], v8 offset:12864
	s_waitcnt lgkmcnt(3)
	v_mfma_f32_32x32x16_bf16 v[100:115], v[206:209], v[164:167], v[100:115]
	ds_read_b128 v[206:209], v8 offset:12896
	s_and_b64 vcc, exec, s[18:19]
	s_cbranch_vccz .Lm_p1
	s_setprio 0
	s_branch .Lm_pd

.Lm_pd:
	s_waitcnt lgkmcnt(3)
	v_mfma_f32_32x32x16_bf16 v[84:99], v[10:13], v[116:119], v[210:225]
	ds_read_b128 v[10:13], v8 offset:12928
	s_waitcnt lgkmcnt(3)
	v_mfma_f32_32x32x16_bf16 v[84:99], v[14:17], v[120:123], v[84:99]
	ds_read_b128 v[14:17], v8 offset:12960
	s_waitcnt lgkmcnt(3)
	v_mfma_f32_32x32x16_bf16 v[84:99], v[202:205], v[124:127], v[84:99]
	ds_read_b128 v[202:205], v8 offset:12992
	s_waitcnt lgkmcnt(3)
	v_mfma_f32_32x32x16_bf16 v[84:99], v[206:209], v[132:135], v[84:99]
	ds_read_b128 v[206:209], v8 offset:13024
	s_waitcnt lgkmcnt(3)
	v_mfma_f32_32x32x16_bf16 v[84:99], v[10:13], v[136:139], v[84:99]
	ds_read_b128 v[10:13], v8 offset:13056
	s_waitcnt lgkmcnt(3)
	v_mfma_f32_32x32x16_bf16 v[84:99], v[14:17], v[140:143], v[84:99]
	ds_read_b128 v[14:17], v8 offset:13088
	s_waitcnt lgkmcnt(3)
	v_mfma_f32_32x32x16_bf16 v[84:99], v[202:205], v[144:147], v[84:99]
	ds_read_b128 v[202:205], v8 offset:13120
	s_waitcnt lgkmcnt(3)
	v_mfma_f32_32x32x16_bf16 v[84:99], v[206:209], v[148:151], v[84:99]
	ds_read_b128 v[206:209], v8 offset:13152
	s_waitcnt lgkmcnt(3)
	v_mfma_f32_32x32x16_bf16 v[84:99], v[10:13], v[152:155], v[84:99]
	ds_read_b64_tr_b16 v[10:11], v197 offset:25600
	ds_read_b64_tr_b16 v[12:13], v197 offset:28160
	s_waitcnt lgkmcnt(4)
	v_mfma_f32_32x32x16_bf16 v[84:99], v[14:17], v[156:159], v[84:99]
	ds_read_b64_tr_b16 v[14:15], v197 offset:25664
	ds_read_b64_tr_b16 v[16:17], v197 offset:28224
	s_waitcnt lgkmcnt(5)
	v_mfma_f32_32x32x16_bf16 v[84:99], v[202:205], v[160:163], v[84:99]
	ds_read_b64_tr_b16 v[202:203], v197 offset:25728
	ds_read_b64_tr_b16 v[204:205], v197 offset:28288
	s_waitcnt lgkmcnt(6)
	v_mfma_f32_32x32x16_bf16 v[84:99], v[206:209], v[164:167], v[84:99]
	ds_read_b64_tr_b16 v[206:207], v197 offset:25792
	ds_read_b64_tr_b16 v[208:209], v197 offset:28352
	v_max3_f32 v235, v100, v101, v102
	v_max3_f32 v235, v235, v103, v104
	v_max3_f32 v235, v235, v105, v106
	v_max3_f32 v235, v235, v107, v108
	v_max3_f32 v235, v235, v109, v110
	v_max3_f32 v235, v235, v111, v112
	v_max3_f32 v235, v235, v113, v114
	s_nop 2
	v_max3_f32 v235, v235, v115, v84
	v_max3_f32 v235, v235, v85, v86
	v_max3_f32 v235, v235, v87, v88
	v_max3_f32 v235, v235, v89, v90
	v_max3_f32 v235, v235, v91, v92
	v_max3_f32 v235, v235, v93, v94
	v_max3_f32 v235, v235, v95, v96
	v_max3_f32 v235, v235, v97, v98
	v_max3_f32 v235, v235, v99, v99
	v_mov_b32_e32 v237, v235
	v_mov_b32_e32 v239, v235
	s_nop 1
	v_permlane32_swap_b32_e32 v237, v239
	v_cndmask_b32_e64 v237, v237, v239, s[4:5]
	v_max_f32_e32 v237, v237, v237
	v_max_f32_e32 v236, v235, v237
	v_cmp_lt_f32_e32 vcc, s29, v236
	s_cbranch_vccnz .Lm_R
.Lm_cont:
	v_exp_f32_e32 v100, v100
	v_exp_f32_e32 v101, v101
	v_exp_f32_e32 v102, v102
	v_exp_f32_e32 v103, v103
	v_exp_f32_e32 v104, v104
	v_exp_f32_e32 v105, v105
	v_exp_f32_e32 v106, v106
	v_exp_f32_e32 v107, v107
	v_add_f32_e32 v234, 0, v100
	v_add_f32_e32 v234, v101, v234
	v_add_f32_e32 v234, v102, v234
	v_add_f32_e32 v234, v103, v234
	v_add_f32_e32 v234, v104, v234
	v_add_f32_e32 v234, v105, v234
	v_add_f32_e32 v234, v106, v234
	v_add_f32_e32 v234, v107, v234
	v_cvt_pk_bf16_f32 v226, v100, v101
	v_cvt_pk_bf16_f32 v227, v102, v103
	v_cvt_pk_bf16_f32 v228, v104, v105
	v_cvt_pk_bf16_f32 v229, v106, v107
	s_waitcnt lgkmcnt(6)
	s_nop 0
	v_mfma_f32_32x32x16_bf16 v[68:83], v[10:13], v[226:229], v[68:83]
	v_exp_f32_e32 v108, v108
	v_exp_f32_e32 v109, v109
	v_exp_f32_e32 v110, v110
	v_exp_f32_e32 v111, v111
	s_waitcnt lgkmcnt(4)
	v_mfma_f32_32x32x16_bf16 v[52:67], v[14:17], v[226:229], v[52:67]
	v_exp_f32_e32 v112, v112
	v_exp_f32_e32 v113, v113
	v_exp_f32_e32 v114, v114
	v_exp_f32_e32 v115, v115
	s_waitcnt lgkmcnt(2)
	v_mfma_f32_32x32x16_bf16 v[36:51], v[202:205], v[226:229], v[36:51]
	v_add_f32_e32 v234, v108, v234
	v_add_f32_e32 v234, v109, v234
	v_add_f32_e32 v234, v110, v234
	v_add_f32_e32 v234, v111, v234
	s_waitcnt lgkmcnt(0)
	v_mfma_f32_32x32x16_bf16 v[20:35], v[206:209], v[226:229], v[20:35]
	v_add_f32_e32 v234, v112, v234
	v_add_f32_e32 v234, v113, v234
	v_add_f32_e32 v234, v114, v234
	v_add_f32_e32 v234, v115, v234
	v_add_f32_e32 v234, v193, v234
	v_cvt_pk_bf16_f32 v230, v108, v109
	v_cvt_pk_bf16_f32 v231, v110, v111
	v_cvt_pk_bf16_f32 v232, v112, v113
	v_cvt_pk_bf16_f32 v233, v114, v115
	ds_read_b64_tr_b16 v[100:101], v197 offset:30720
	ds_read_b64_tr_b16 v[102:103], v197 offset:33280
	ds_read_b64_tr_b16 v[104:105], v197 offset:30784
	ds_read_b64_tr_b16 v[106:107], v197 offset:33344
	ds_read_b64_tr_b16 v[108:109], v197 offset:30848
	ds_read_b64_tr_b16 v[110:111], v197 offset:33408
	ds_read_b64_tr_b16 v[112:113], v197 offset:30912
	ds_read_b64_tr_b16 v[114:115], v197 offset:33472
	ds_read_b64_tr_b16 v[10:11], v197 offset:35840
	ds_read_b64_tr_b16 v[12:13], v197 offset:38400
	ds_read_b64_tr_b16 v[14:15], v197 offset:35904
	ds_read_b64_tr_b16 v[16:17], v197 offset:38464
	ds_read_b64_tr_b16 v[202:203], v197 offset:35968
	ds_read_b64_tr_b16 v[204:205], v197 offset:38528
	ds_read_b64_tr_b16 v[206:207], v197 offset:36032
	ds_read_b64_tr_b16 v[208:209], v197 offset:38592
	v_exp_f32_e32 v84, v84
	v_exp_f32_e32 v85, v85
	v_exp_f32_e32 v86, v86
	v_exp_f32_e32 v87, v87
	v_exp_f32_e32 v88, v88
	v_exp_f32_e32 v89, v89
	v_exp_f32_e32 v90, v90
	v_exp_f32_e32 v91, v91
	v_add_f32_e32 v240, 0, v84
	v_add_f32_e32 v240, v85, v240
	v_add_f32_e32 v240, v86, v240
	v_add_f32_e32 v240, v87, v240
	v_add_f32_e32 v240, v88, v240
	v_add_f32_e32 v240, v89, v240
	v_add_f32_e32 v240, v90, v240
	v_add_f32_e32 v240, v91, v240
	v_cvt_pk_bf16_f32 v226, v84, v85
	v_cvt_pk_bf16_f32 v227, v86, v87
	v_cvt_pk_bf16_f32 v228, v88, v89
	v_cvt_pk_bf16_f32 v229, v90, v91
	s_waitcnt lgkmcnt(14)
	v_mfma_f32_32x32x16_bf16 v[68:83], v[100:103], v[230:233], v[68:83]
	v_exp_f32_e32 v92, v92
	v_exp_f32_e32 v93, v93
	v_exp_f32_e32 v94, v94
	v_exp_f32_e32 v95, v95
	s_waitcnt lgkmcnt(12)
	v_mfma_f32_32x32x16_bf16 v[52:67], v[104:107], v[230:233], v[52:67]
	v_exp_f32_e32 v96, v96
	v_exp_f32_e32 v97, v97
	v_exp_f32_e32 v98, v98
	v_exp_f32_e32 v99, v99
	s_waitcnt lgkmcnt(10)
	v_mfma_f32_32x32x16_bf16 v[36:51], v[108:111], v[230:233], v[36:51]
	v_add_f32_e32 v240, v92, v240
	v_add_f32_e32 v240, v93, v240
	v_add_f32_e32 v240, v94, v240
	v_add_f32_e32 v240, v95, v240
	s_waitcnt lgkmcnt(8)
	v_mfma_f32_32x32x16_bf16 v[20:35], v[112:115], v[230:233], v[20:35]
	ds_read_b64_tr_b16 v[100:101], v197 offset:40960
	ds_read_b64_tr_b16 v[102:103], v197 offset:43520
	ds_read_b64_tr_b16 v[104:105], v197 offset:41024
	ds_read_b64_tr_b16 v[106:107], v197 offset:43584
	ds_read_b64_tr_b16 v[108:109], v197 offset:41088
	ds_read_b64_tr_b16 v[110:111], v197 offset:43648
	ds_read_b64_tr_b16 v[112:113], v197 offset:41152
	ds_read_b64_tr_b16 v[114:115], v197 offset:43712
	v_add_f32_e32 v240, v96, v240
	v_add_f32_e32 v240, v97, v240
	v_add_f32_e32 v240, v98, v240
	v_add_f32_e32 v240, v99, v240
	v_cvt_pk_bf16_f32 v230, v92, v93
	v_cvt_pk_bf16_f32 v231, v94, v95
	v_cvt_pk_bf16_f32 v232, v96, v97
	v_cvt_pk_bf16_f32 v233, v98, v99
	v_add_f32_e32 v193, v234, v240
	s_waitcnt lgkmcnt(14)
	v_mfma_f32_32x32x16_bf16 v[68:83], v[10:13], v[226:229], v[68:83]
	s_waitcnt lgkmcnt(12)
	v_mfma_f32_32x32x16_bf16 v[52:67], v[14:17], v[226:229], v[52:67]
	s_waitcnt lgkmcnt(10)
	v_mfma_f32_32x32x16_bf16 v[36:51], v[202:205], v[226:229], v[36:51]
	s_waitcnt lgkmcnt(8)
	v_mfma_f32_32x32x16_bf16 v[20:35], v[206:209], v[226:229], v[20:35]
	s_waitcnt lgkmcnt(6)
	v_mfma_f32_32x32x16_bf16 v[68:83], v[100:103], v[230:233], v[68:83]
	s_waitcnt lgkmcnt(4)
	v_mfma_f32_32x32x16_bf16 v[52:67], v[104:107], v[230:233], v[52:67]
	s_waitcnt lgkmcnt(2)
	v_mfma_f32_32x32x16_bf16 v[36:51], v[108:111], v[230:233], v[36:51]
	s_waitcnt lgkmcnt(0)
	v_mfma_f32_32x32x16_bf16 v[20:35], v[112:115], v[230:233], v[20:35]

.Lm_R:
	v_max_f32_e32 v236, v236, v236
	v_max_f32_e32 v236, 0, v236
	v_exp_f32_e64 v238, -v236
	v_pk_add_f32 v[100:101], v[100:101], v[236:237] op_sel_hi:[1,0] neg_lo:[0,1] neg_hi:[0,1]
	v_pk_add_f32 v[102:103], v[102:103], v[236:237] op_sel_hi:[1,0] neg_lo:[0,1] neg_hi:[0,1]
	v_pk_add_f32 v[104:105], v[104:105], v[236:237] op_sel_hi:[1,0] neg_lo:[0,1] neg_hi:[0,1]
	v_pk_add_f32 v[106:107], v[106:107], v[236:237] op_sel_hi:[1,0] neg_lo:[0,1] neg_hi:[0,1]
	v_pk_add_f32 v[108:109], v[108:109], v[236:237] op_sel_hi:[1,0] neg_lo:[0,1] neg_hi:[0,1]
	v_pk_add_f32 v[110:111], v[110:111], v[236:237] op_sel_hi:[1,0] neg_lo:[0,1] neg_hi:[0,1]
	v_pk_add_f32 v[112:113], v[112:113], v[236:237] op_sel_hi:[1,0] neg_lo:[0,1] neg_hi:[0,1]
	v_pk_add_f32 v[114:115], v[114:115], v[236:237] op_sel_hi:[1,0] neg_lo:[0,1] neg_hi:[0,1]
	v_pk_add_f32 v[84:85], v[84:85], v[236:237] op_sel_hi:[1,0] neg_lo:[0,1] neg_hi:[0,1]
	v_pk_add_f32 v[86:87], v[86:87], v[236:237] op_sel_hi:[1,0] neg_lo:[0,1] neg_hi:[0,1]
	v_pk_add_f32 v[88:89], v[88:89], v[236:237] op_sel_hi:[1,0] neg_lo:[0,1] neg_hi:[0,1]
	v_pk_add_f32 v[90:91], v[90:91], v[236:237] op_sel_hi:[1,0] neg_lo:[0,1] neg_hi:[0,1]
	v_pk_add_f32 v[92:93], v[92:93], v[236:237] op_sel_hi:[1,0] neg_lo:[0,1] neg_hi:[0,1]
	v_pk_add_f32 v[94:95], v[94:95], v[236:237] op_sel_hi:[1,0] neg_lo:[0,1] neg_hi:[0,1]
	v_pk_add_f32 v[96:97], v[96:97], v[236:237] op_sel_hi:[1,0] neg_lo:[0,1] neg_hi:[0,1]
	v_pk_add_f32 v[98:99], v[98:99], v[236:237] op_sel_hi:[1,0] neg_lo:[0,1] neg_hi:[0,1]
	v_pk_add_f32 v[210:211], v[210:211], v[236:237] op_sel_hi:[1,0] neg_lo:[0,1] neg_hi:[0,1]
	v_pk_add_f32 v[212:213], v[212:213], v[236:237] op_sel_hi:[1,0] neg_lo:[0,1] neg_hi:[0,1]
	v_pk_add_f32 v[214:215], v[214:215], v[236:237] op_sel_hi:[1,0] neg_lo:[0,1] neg_hi:[0,1]
	v_pk_add_f32 v[216:217], v[216:217], v[236:237] op_sel_hi:[1,0] neg_lo:[0,1] neg_hi:[0,1]
	v_pk_add_f32 v[218:219], v[218:219], v[236:237] op_sel_hi:[1,0] neg_lo:[0,1] neg_hi:[0,1]
	v_pk_add_f32 v[220:221], v[220:221], v[236:237] op_sel_hi:[1,0] neg_lo:[0,1] neg_hi:[0,1]
	v_pk_add_f32 v[222:223], v[222:223], v[236:237] op_sel_hi:[1,0] neg_lo:[0,1] neg_hi:[0,1]
	v_pk_add_f32 v[224:225], v[224:225], v[236:237] op_sel_hi:[1,0] neg_lo:[0,1] neg_hi:[0,1]
	v_mul_f32_e32 v193, v193, v238
	v_pk_mul_f32 v[68:69], v[68:69], v[238:239] op_sel_hi:[1,0]
	v_pk_mul_f32 v[70:71], v[70:71], v[238:239] op_sel_hi:[1,0]
	v_pk_mul_f32 v[72:73], v[72:73], v[238:239] op_sel_hi:[1,0]
	v_pk_mul_f32 v[74:75], v[74:75], v[238:239] op_sel_hi:[1,0]
	v_pk_mul_f32 v[76:77], v[76:77], v[238:239] op_sel_hi:[1,0]
	v_pk_mul_f32 v[78:79], v[78:79], v[238:239] op_sel_hi:[1,0]
	v_pk_mul_f32 v[80:81], v[80:81], v[238:239] op_sel_hi:[1,0]
	v_pk_mul_f32 v[82:83], v[82:83], v[238:239] op_sel_hi:[1,0]
	v_pk_mul_f32 v[52:53], v[52:53], v[238:239] op_sel_hi:[1,0]
	v_pk_mul_f32 v[54:55], v[54:55], v[238:239] op_sel_hi:[1,0]
	v_pk_mul_f32 v[56:57], v[56:57], v[238:239] op_sel_hi:[1,0]
	v_pk_mul_f32 v[58:59], v[58:59], v[238:239] op_sel_hi:[1,0]
	v_pk_mul_f32 v[60:61], v[60:61], v[238:239] op_sel_hi:[1,0]
	v_pk_mul_f32 v[62:63], v[62:63], v[238:239] op_sel_hi:[1,0]
	v_pk_mul_f32 v[64:65], v[64:65], v[238:239] op_sel_hi:[1,0]
	v_pk_mul_f32 v[66:67], v[66:67], v[238:239] op_sel_hi:[1,0]
	v_pk_mul_f32 v[36:37], v[36:37], v[238:239] op_sel_hi:[1,0]
	v_pk_mul_f32 v[38:39], v[38:39], v[238:239] op_sel_hi:[1,0]
	v_pk_mul_f32 v[40:41], v[40:41], v[238:239] op_sel_hi:[1,0]
	v_pk_mul_f32 v[42:43], v[42:43], v[238:239] op_sel_hi:[1,0]
	v_pk_mul_f32 v[44:45], v[44:45], v[238:239] op_sel_hi:[1,0]
	v_pk_mul_f32 v[46:47], v[46:47], v[238:239] op_sel_hi:[1,0]
	v_pk_mul_f32 v[48:49], v[48:49], v[238:239] op_sel_hi:[1,0]
	v_pk_mul_f32 v[50:51], v[50:51], v[238:239] op_sel_hi:[1,0]
	v_pk_mul_f32 v[20:21], v[20:21], v[238:239] op_sel_hi:[1,0]
	v_pk_mul_f32 v[22:23], v[22:23], v[238:239] op_sel_hi:[1,0]
	v_pk_mul_f32 v[24:25], v[24:25], v[238:239] op_sel_hi:[1,0]
	v_pk_mul_f32 v[26:27], v[26:27], v[238:239] op_sel_hi:[1,0]
	v_pk_mul_f32 v[28:29], v[28:29], v[238:239] op_sel_hi:[1,0]
	v_pk_mul_f32 v[30:31], v[30:31], v[238:239] op_sel_hi:[1,0]
	v_pk_mul_f32 v[32:33], v[32:33], v[238:239] op_sel_hi:[1,0]
	v_pk_mul_f32 v[34:35], v[34:35], v[238:239] op_sel_hi:[1,0]
	v_add_f32_e32 v192, v192, v236
	s_branch .Lm_cont
